# residual (down/out-proj) GEMM epilogue: all 16 residual-stream tile loads issued up front into K-loop scratch registers with counted vmcnt waits, instead of a serial load-wait-use chain
# speedup vs baseline: 1.0249x; 1.0030x over previous
.LBB0_858:
	v_lshl_add_u32 v140, s51, 8, v144
	v_ashrrev_i32_e32 v141, 31, v140
	v_lshl_or_b32 v138, s36, 8, v146
	v_lshlrev_b64 v[142:143], 11, v[140:141]
	v_ashrrev_i32_e32 v139, 31, v138
	v_lshl_add_u64 v[142:143], s[80:81], 0, v[142:143]
	v_lshl_add_u64 v[142:143], v[138:139], 1, v[142:143]
	global_load_dwordx4 v[148:151], v[142:143], off
	global_load_dwordx4 v[156:159], v[142:143], off offset:256
	s_mov_b64 s[52:53], 0x8000
	v_lshl_add_u64 v[226:227], s[52:53], 0, v[142:143]
	global_load_dwordx4 v[160:163], v[226:227], off
	global_load_dwordx4 v[164:167], v[226:227], off offset:256
	s_mov_b64 s[52:53], 0x10000
	v_lshl_add_u64 v[226:227], s[52:53], 0, v[142:143]
	global_load_dwordx4 v[168:171], v[226:227], off
	global_load_dwordx4 v[172:175], v[226:227], off offset:256
	s_mov_b64 s[52:53], 0x18000
	v_lshl_add_u64 v[226:227], s[52:53], 0, v[142:143]
	global_load_dwordx4 v[176:179], v[226:227], off
	global_load_dwordx4 v[180:183], v[226:227], off offset:256
	s_mov_b64 s[52:53], 0x40000
	v_lshl_add_u64 v[226:227], s[52:53], 0, v[142:143]
	global_load_dwordx4 v[184:187], v[226:227], off
	global_load_dwordx4 v[188:191], v[226:227], off offset:256
	s_mov_b64 s[52:53], 0x48000
	v_lshl_add_u64 v[226:227], s[52:53], 0, v[142:143]
	global_load_dwordx4 v[192:195], v[226:227], off
	global_load_dwordx4 v[204:207], v[226:227], off offset:256
	s_mov_b64 s[52:53], 0x50000
	v_lshl_add_u64 v[226:227], s[52:53], 0, v[142:143]
	global_load_dwordx4 v[208:211], v[226:227], off
	global_load_dwordx4 v[212:215], v[226:227], off offset:256
	s_mov_b64 s[52:53], 0x58000
	v_lshl_add_u64 v[226:227], s[52:53], 0, v[142:143]
	global_load_dwordx4 v[216:219], v[226:227], off
	global_load_dwordx4 v[228:231], v[226:227], off offset:256
	s_lshl_b32 s34, s36, 2
	s_ashr_i32 s35, s34, 31
	s_waitcnt vmcnt(15)
	v_lshlrev_b32_e32 v152, 16, v148
	v_fmac_f32_e32 v152, s2, v124
	v_and_b32_e32 v124, 0xffff0000, v148
	v_fmac_f32_e32 v124, s2, v125
	v_cvt_pk_bf16_f32 v124, v152, v124
	s_nop 0
	v_and_b32_e32 v148, 0xffff0000, v124
	v_lshlrev_b32_e32 v125, 16, v124
	v_mul_f32_e32 v148, v148, v148
	v_fmac_f32_e32 v148, v125, v125
	v_lshlrev_b32_e32 v125, 16, v149
	v_fmac_f32_e32 v125, s2, v126
	v_and_b32_e32 v126, 0xffff0000, v149
	v_fmac_f32_e32 v126, s2, v127
	v_cvt_pk_bf16_f32 v125, v125, v126
	s_nop 0
	v_and_b32_e32 v127, 0xffff0000, v125
	v_lshlrev_b32_e32 v126, 16, v125
	v_mul_f32_e32 v127, v127, v127
	v_fmac_f32_e32 v127, v126, v126
	v_lshlrev_b32_e32 v126, 16, v150
	v_fmac_f32_e32 v126, s2, v120
	v_and_b32_e32 v120, 0xffff0000, v150
	v_fmac_f32_e32 v120, s2, v121
	v_cvt_pk_bf16_f32 v126, v126, v120
	v_add_f32_e32 v127, v148, v127
	v_and_b32_e32 v121, 0xffff0000, v126
	v_lshlrev_b32_e32 v120, 16, v126
	v_mul_f32_e32 v121, v121, v121
	v_fmac_f32_e32 v121, v120, v120
	v_add_f32_e32 v120, v127, v121
	v_lshlrev_b32_e32 v121, 16, v151
	v_fmac_f32_e32 v121, s2, v122
	v_and_b32_e32 v122, 0xffff0000, v151
	v_fmac_f32_e32 v122, s2, v123
	v_cvt_pk_bf16_f32 v127, v121, v122
	global_store_dwordx4 v[142:143], v[124:127], off
	v_and_b32_e32 v122, 0xffff0000, v127
	v_lshlrev_b32_e32 v121, 16, v127
	v_mul_f32_e32 v122, v122, v122
	v_fmac_f32_e32 v122, v121, v121
	v_add_f32_e32 v148, v120, v122
	s_waitcnt vmcnt(15)
	v_mov_b64_e32 v[120:121], v[156:157]
	v_mov_b64_e32 v[122:123], v[158:159]
	v_lshlrev_b32_e32 v124, 16, v120
	v_fmac_f32_e32 v124, s2, v116
	v_and_b32_e32 v116, 0xffff0000, v120
	v_fmac_f32_e32 v116, s2, v117
	v_cvt_pk_bf16_f32 v116, v124, v116
	s_nop 0
	v_and_b32_e32 v120, 0xffff0000, v116
	v_lshlrev_b32_e32 v117, 16, v116
	v_mul_f32_e32 v120, v120, v120
	v_fmac_f32_e32 v120, v117, v117
	v_lshlrev_b32_e32 v117, 16, v121
	v_fmac_f32_e32 v117, s2, v118
	v_and_b32_e32 v118, 0xffff0000, v121
	v_fmac_f32_e32 v118, s2, v119
	v_cvt_pk_bf16_f32 v117, v117, v118
	v_add_f32_e32 v120, v148, v120
	v_and_b32_e32 v119, 0xffff0000, v117
	v_lshlrev_b32_e32 v118, 16, v117
	v_mul_f32_e32 v119, v119, v119
	v_fmac_f32_e32 v119, v118, v118
	v_lshlrev_b32_e32 v118, 16, v122
	v_fmac_f32_e32 v118, s2, v112
	v_and_b32_e32 v112, 0xffff0000, v122
	v_fmac_f32_e32 v112, s2, v113
	v_cvt_pk_bf16_f32 v118, v118, v112
	v_add_f32_e32 v119, v120, v119
	v_and_b32_e32 v113, 0xffff0000, v118
	v_lshlrev_b32_e32 v112, 16, v118
	v_mul_f32_e32 v113, v113, v113
	v_fmac_f32_e32 v113, v112, v112
	v_add_f32_e32 v112, v119, v113
	v_lshlrev_b32_e32 v113, 16, v123
	v_fmac_f32_e32 v113, s2, v114
	v_and_b32_e32 v114, 0xffff0000, v123
	v_fmac_f32_e32 v114, s2, v115
	v_cvt_pk_bf16_f32 v119, v113, v114
	global_store_dwordx4 v[142:143], v[116:119], off offset:256
	v_and_b32_e32 v114, 0xffff0000, v119
	v_lshlrev_b32_e32 v113, 16, v119
	v_mul_f32_e32 v114, v114, v114
	v_fmac_f32_e32 v114, v113, v113
	v_add_f32_e32 v112, v112, v114
	v_and_b32_e32 v114, 64, v222
	v_xor_b32_e32 v113, 16, v222
	v_add_u32_e32 v115, 64, v114
	v_cmp_lt_i32_e32 vcc, v113, v115
	s_nop 1
	v_cndmask_b32_e32 v113, v222, v113, vcc
	v_lshlrev_b32_e32 v114, 2, v113
	ds_bpermute_b32 v113, v114, v112
	s_waitcnt lgkmcnt(0)
	v_add_f32_e32 v112, v112, v113
	v_xor_b32_e32 v113, 32, v222
	v_cmp_lt_i32_e32 vcc, v113, v115
	s_nop 1
	v_cndmask_b32_e32 v113, v222, v113, vcc
	v_lshlrev_b32_e32 v115, 2, v113
	ds_bpermute_b32 v113, v115, v112
	s_and_saveexec_b64 s[44:45], s[40:41]
	s_cbranch_execz .LBB0_860
	v_lshlrev_b64 v[116:117], 6, v[140:141]
	v_lshl_add_u64 v[116:117], s[20:21], 0, v[116:117]
	v_lshl_add_u64 v[116:117], s[34:35], 2, v[116:117]
	s_lshl_b32 s36, s27, 2
	v_lshl_add_u64 v[116:117], v[116:117], 0, s[36:37]
	s_waitcnt lgkmcnt(0)
	v_add_f32_e32 v112, v112, v113
	global_store_dword v[116:117], v112, off
.LBB0_860:
	s_or_b64 exec, exec, s[44:45]
	v_or_b32_e32 v112, 16, v140
	s_waitcnt lgkmcnt(0)
	v_ashrrev_i32_e32 v113, 31, v112
	v_lshlrev_b64 v[116:117], 11, v[112:113]
	v_lshl_add_u64 v[116:117], s[80:81], 0, v[116:117]
	v_lshl_add_u64 v[120:121], v[138:139], 1, v[116:117]
	s_waitcnt vmcnt(16)
	v_mov_b64_e32 v[116:117], v[160:161]
	v_mov_b64_e32 v[118:119], v[162:163]
	v_lshlrev_b32_e32 v122, 16, v116
	v_and_b32_e32 v116, 0xffff0000, v116
	v_lshlrev_b32_e32 v123, 16, v117
	v_and_b32_e32 v117, 0xffff0000, v117
	v_lshlrev_b32_e32 v124, 16, v118
	v_and_b32_e32 v118, 0xffff0000, v118
	v_lshlrev_b32_e32 v125, 16, v119
	v_and_b32_e32 v119, 0xffff0000, v119
	v_fmac_f32_e32 v122, s2, v108
	v_fmac_f32_e32 v116, s2, v109
	v_fmac_f32_e32 v123, s2, v110
	v_fmac_f32_e32 v117, s2, v111
	v_fmac_f32_e32 v124, s2, v104
	v_fmac_f32_e32 v118, s2, v105
	v_fmac_f32_e32 v125, s2, v106
	v_fmac_f32_e32 v119, s2, v107
	v_cvt_pk_bf16_f32 v104, v122, v116
	v_cvt_pk_bf16_f32 v105, v123, v117
	v_cvt_pk_bf16_f32 v106, v124, v118
	v_cvt_pk_bf16_f32 v107, v125, v119
	v_and_b32_e32 v117, 0xffff0000, v104
	v_and_b32_e32 v119, 0xffff0000, v105
	v_lshlrev_b32_e32 v116, 16, v104
	v_lshlrev_b32_e32 v118, 16, v105
	v_and_b32_e32 v123, 0xffff0000, v106
	global_store_dwordx4 v[120:121], v[104:107], off
	v_lshlrev_b32_e32 v122, 16, v106
	v_and_b32_e32 v125, 0xffff0000, v107
	v_mul_f32_e32 v104, v117, v117
	v_mul_f32_e32 v105, v119, v119
	v_mul_f32_e32 v106, v123, v123
	v_fmac_f32_e32 v104, v116, v116
	v_fmac_f32_e32 v105, v118, v118
	v_lshlrev_b32_e32 v124, 16, v107
	v_mul_f32_e32 v107, v125, v125
	v_fmac_f32_e32 v106, v122, v122
	v_add_f32_e32 v104, v104, v105
	v_fmac_f32_e32 v107, v124, v124
	v_add_f32_e32 v104, v104, v106
	v_add_f32_e32 v104, v104, v107
	s_waitcnt vmcnt(16)
	v_mov_b64_e32 v[108:109], v[164:165]
	v_mov_b64_e32 v[110:111], v[166:167]
	v_lshlrev_b32_e32 v105, 16, v108
	v_and_b32_e32 v106, 0xffff0000, v108
	v_lshlrev_b32_e32 v107, 16, v109
	v_and_b32_e32 v108, 0xffff0000, v109
	v_lshlrev_b32_e32 v109, 16, v110
	v_and_b32_e32 v110, 0xffff0000, v110
	v_lshlrev_b32_e32 v116, 16, v111
	v_and_b32_e32 v111, 0xffff0000, v111
	v_fmac_f32_e32 v105, s2, v100
	v_fmac_f32_e32 v106, s2, v101
	v_fmac_f32_e32 v110, s2, v97
	v_fmac_f32_e32 v116, s2, v98
	v_cvt_pk_bf16_f32 v98, v105, v106
	v_fmac_f32_e32 v107, s2, v102
	v_and_b32_e32 v97, 0xffff0000, v98
	v_fmac_f32_e32 v108, s2, v103
	v_fmac_f32_e32 v109, s2, v96
	v_fmac_f32_e32 v111, s2, v99
	v_cvt_pk_bf16_f32 v99, v107, v108
	v_lshlrev_b32_e32 v96, 16, v98
	v_and_b32_e32 v103, 0xffff0000, v99
	v_mul_f32_e32 v97, v97, v97
	v_cvt_pk_bf16_f32 v100, v109, v110
	v_lshlrev_b32_e32 v102, 16, v99
	v_and_b32_e32 v106, 0xffff0000, v100
	v_mul_f32_e32 v103, v103, v103
	v_fmac_f32_e32 v97, v96, v96
	v_cvt_pk_bf16_f32 v101, v116, v111
	v_lshlrev_b32_e32 v105, 16, v100
	v_and_b32_e32 v108, 0xffff0000, v101
	v_mul_f32_e32 v106, v106, v106
	v_fmac_f32_e32 v103, v102, v102
	v_add_f32_e32 v96, v104, v97
	v_lshlrev_b32_e32 v107, 16, v101
	v_mul_f32_e32 v108, v108, v108
	v_fmac_f32_e32 v106, v105, v105
	v_add_f32_e32 v96, v96, v103
	v_add_f32_e32 v96, v96, v106
	v_fmac_f32_e32 v108, v107, v107
	v_add_f32_e32 v96, v96, v108
	ds_bpermute_b32 v97, v114, v96
	global_store_dwordx4 v[120:121], v[98:101], off offset:256
	s_waitcnt lgkmcnt(0)
	v_add_f32_e32 v96, v96, v97
	ds_bpermute_b32 v97, v115, v96
	s_and_saveexec_b64 s[44:45], s[40:41]
	s_cbranch_execz .LBB0_862
	v_lshlrev_b64 v[98:99], 6, v[112:113]
	v_lshl_add_u64 v[98:99], s[20:21], 0, v[98:99]
	v_lshl_add_u64 v[98:99], s[34:35], 2, v[98:99]
	s_lshl_b32 s36, s27, 2
	v_lshl_add_u64 v[98:99], v[98:99], 0, s[36:37]
	s_waitcnt lgkmcnt(0)
	v_add_f32_e32 v96, v96, v97
	global_store_dword v[98:99], v96, off
.LBB0_862:
	s_or_b64 exec, exec, s[44:45]
	v_or_b32_e32 v96, 32, v140
	s_waitcnt lgkmcnt(0)
	v_ashrrev_i32_e32 v97, 31, v96
	v_lshlrev_b64 v[98:99], 11, v[96:97]
	v_lshl_add_u64 v[98:99], s[80:81], 0, v[98:99]
	v_lshl_add_u64 v[102:103], v[138:139], 1, v[98:99]
	s_waitcnt vmcnt(17)
	v_mov_b64_e32 v[98:99], v[168:169]
	v_mov_b64_e32 v[100:101], v[170:171]
	v_lshlrev_b32_e32 v104, 16, v98
	v_and_b32_e32 v98, 0xffff0000, v98
	v_lshlrev_b32_e32 v105, 16, v99
	v_and_b32_e32 v99, 0xffff0000, v99
	v_lshlrev_b32_e32 v106, 16, v100
	v_and_b32_e32 v100, 0xffff0000, v100
	v_lshlrev_b32_e32 v107, 16, v101
	v_and_b32_e32 v101, 0xffff0000, v101
	v_fmac_f32_e32 v104, s2, v92
	v_fmac_f32_e32 v98, s2, v93
	v_fmac_f32_e32 v105, s2, v94
	v_fmac_f32_e32 v99, s2, v95
	v_fmac_f32_e32 v106, s2, v88
	v_fmac_f32_e32 v100, s2, v89
	v_fmac_f32_e32 v107, s2, v90
	v_fmac_f32_e32 v101, s2, v91
	v_cvt_pk_bf16_f32 v88, v104, v98
	v_cvt_pk_bf16_f32 v89, v105, v99
	v_cvt_pk_bf16_f32 v90, v106, v100
	v_cvt_pk_bf16_f32 v91, v107, v101
	v_and_b32_e32 v99, 0xffff0000, v88
	v_and_b32_e32 v101, 0xffff0000, v89
	v_lshlrev_b32_e32 v98, 16, v88
	v_lshlrev_b32_e32 v100, 16, v89
	v_and_b32_e32 v105, 0xffff0000, v90
	global_store_dwordx4 v[102:103], v[88:91], off
	v_lshlrev_b32_e32 v104, 16, v90
	v_and_b32_e32 v107, 0xffff0000, v91
	v_mul_f32_e32 v88, v99, v99
	v_mul_f32_e32 v89, v101, v101
	v_mul_f32_e32 v90, v105, v105
	v_fmac_f32_e32 v88, v98, v98
	v_fmac_f32_e32 v89, v100, v100
	v_lshlrev_b32_e32 v106, 16, v91
	v_mul_f32_e32 v91, v107, v107
	v_fmac_f32_e32 v90, v104, v104
	v_add_f32_e32 v88, v88, v89
	v_fmac_f32_e32 v91, v106, v106
	v_add_f32_e32 v88, v88, v90
	v_add_f32_e32 v88, v88, v91
	s_waitcnt vmcnt(17)
	v_mov_b64_e32 v[92:93], v[172:173]
	v_mov_b64_e32 v[94:95], v[174:175]
	v_lshlrev_b32_e32 v89, 16, v92
	v_and_b32_e32 v90, 0xffff0000, v92
	v_lshlrev_b32_e32 v91, 16, v93
	v_and_b32_e32 v92, 0xffff0000, v93
	v_lshlrev_b32_e32 v93, 16, v94
	v_and_b32_e32 v94, 0xffff0000, v94
	v_lshlrev_b32_e32 v98, 16, v95
	v_and_b32_e32 v95, 0xffff0000, v95
	v_fmac_f32_e32 v89, s2, v84
	v_fmac_f32_e32 v90, s2, v85
	v_fmac_f32_e32 v94, s2, v81
	v_fmac_f32_e32 v98, s2, v82
	v_cvt_pk_bf16_f32 v82, v89, v90
	v_fmac_f32_e32 v91, s2, v86
	v_and_b32_e32 v81, 0xffff0000, v82
	v_fmac_f32_e32 v92, s2, v87
	v_fmac_f32_e32 v93, s2, v80
	v_fmac_f32_e32 v95, s2, v83
	v_cvt_pk_bf16_f32 v83, v91, v92
	v_lshlrev_b32_e32 v80, 16, v82
	v_and_b32_e32 v87, 0xffff0000, v83
	v_mul_f32_e32 v81, v81, v81
	v_cvt_pk_bf16_f32 v84, v93, v94
	v_lshlrev_b32_e32 v86, 16, v83
	v_and_b32_e32 v90, 0xffff0000, v84
	v_mul_f32_e32 v87, v87, v87
	v_fmac_f32_e32 v81, v80, v80
	v_cvt_pk_bf16_f32 v85, v98, v95
	v_lshlrev_b32_e32 v89, 16, v84
	v_and_b32_e32 v92, 0xffff0000, v85
	v_mul_f32_e32 v90, v90, v90
	v_fmac_f32_e32 v87, v86, v86
	v_add_f32_e32 v80, v88, v81
	v_lshlrev_b32_e32 v91, 16, v85
	v_mul_f32_e32 v92, v92, v92
	v_fmac_f32_e32 v90, v89, v89
	v_add_f32_e32 v80, v80, v87
	v_add_f32_e32 v80, v80, v90
	v_fmac_f32_e32 v92, v91, v91
	v_add_f32_e32 v80, v80, v92
	ds_bpermute_b32 v81, v114, v80
	global_store_dwordx4 v[102:103], v[82:85], off offset:256
	s_waitcnt lgkmcnt(0)
	v_add_f32_e32 v80, v80, v81
	ds_bpermute_b32 v81, v115, v80
	s_and_saveexec_b64 s[44:45], s[40:41]
	s_cbranch_execz .LBB0_864
	v_lshlrev_b64 v[82:83], 6, v[96:97]
	v_lshl_add_u64 v[82:83], s[20:21], 0, v[82:83]
	v_lshl_add_u64 v[82:83], s[34:35], 2, v[82:83]
	s_lshl_b32 s36, s27, 2
	v_lshl_add_u64 v[82:83], v[82:83], 0, s[36:37]
	s_waitcnt lgkmcnt(0)
	v_add_f32_e32 v80, v80, v81
	global_store_dword v[82:83], v80, off
.LBB0_864:
	s_or_b64 exec, exec, s[44:45]
	v_or_b32_e32 v80, 48, v140
	s_waitcnt lgkmcnt(0)
	v_ashrrev_i32_e32 v81, 31, v80
	v_lshlrev_b64 v[82:83], 11, v[80:81]
	v_lshl_add_u64 v[82:83], s[80:81], 0, v[82:83]
	v_lshl_add_u64 v[86:87], v[138:139], 1, v[82:83]
	s_waitcnt vmcnt(18)
	v_mov_b64_e32 v[82:83], v[176:177]
	v_mov_b64_e32 v[84:85], v[178:179]
	v_lshlrev_b32_e32 v88, 16, v82
	v_and_b32_e32 v82, 0xffff0000, v82
	v_lshlrev_b32_e32 v89, 16, v83
	v_and_b32_e32 v83, 0xffff0000, v83
	v_lshlrev_b32_e32 v90, 16, v84
	v_and_b32_e32 v84, 0xffff0000, v84
	v_lshlrev_b32_e32 v91, 16, v85
	v_and_b32_e32 v85, 0xffff0000, v85
	v_fmac_f32_e32 v88, s2, v76
	v_fmac_f32_e32 v82, s2, v77
	v_fmac_f32_e32 v89, s2, v78
	v_fmac_f32_e32 v83, s2, v79
	v_fmac_f32_e32 v90, s2, v72
	v_fmac_f32_e32 v84, s2, v73
	v_fmac_f32_e32 v91, s2, v74
	v_fmac_f32_e32 v85, s2, v75
	v_cvt_pk_bf16_f32 v72, v88, v82
	v_cvt_pk_bf16_f32 v73, v89, v83
	v_cvt_pk_bf16_f32 v74, v90, v84
	v_cvt_pk_bf16_f32 v75, v91, v85
	v_and_b32_e32 v83, 0xffff0000, v72
	v_and_b32_e32 v85, 0xffff0000, v73
	v_lshlrev_b32_e32 v82, 16, v72
	v_lshlrev_b32_e32 v84, 16, v73
	v_and_b32_e32 v89, 0xffff0000, v74
	global_store_dwordx4 v[86:87], v[72:75], off
	v_lshlrev_b32_e32 v88, 16, v74
	v_and_b32_e32 v91, 0xffff0000, v75
	v_mul_f32_e32 v72, v83, v83
	v_mul_f32_e32 v73, v85, v85
	v_mul_f32_e32 v74, v89, v89
	v_fmac_f32_e32 v72, v82, v82
	v_fmac_f32_e32 v73, v84, v84
	v_lshlrev_b32_e32 v90, 16, v75
	v_mul_f32_e32 v75, v91, v91
	v_fmac_f32_e32 v74, v88, v88
	v_add_f32_e32 v72, v72, v73
	v_fmac_f32_e32 v75, v90, v90
	v_add_f32_e32 v72, v72, v74
	v_add_f32_e32 v72, v72, v75
	s_waitcnt vmcnt(18)
	v_mov_b64_e32 v[76:77], v[180:181]
	v_mov_b64_e32 v[78:79], v[182:183]
	v_lshlrev_b32_e32 v73, 16, v76
	v_and_b32_e32 v74, 0xffff0000, v76
	v_lshlrev_b32_e32 v75, 16, v77
	v_and_b32_e32 v76, 0xffff0000, v77
	v_lshlrev_b32_e32 v77, 16, v78
	v_and_b32_e32 v78, 0xffff0000, v78
	v_lshlrev_b32_e32 v82, 16, v79
	v_and_b32_e32 v79, 0xffff0000, v79
	v_fmac_f32_e32 v73, s2, v68
	v_fmac_f32_e32 v74, s2, v69
	v_fmac_f32_e32 v78, s2, v65
	v_fmac_f32_e32 v82, s2, v66
	v_cvt_pk_bf16_f32 v66, v73, v74
	v_fmac_f32_e32 v75, s2, v70
	v_and_b32_e32 v65, 0xffff0000, v66
	v_fmac_f32_e32 v76, s2, v71
	v_fmac_f32_e32 v77, s2, v64
	v_fmac_f32_e32 v79, s2, v67
	v_cvt_pk_bf16_f32 v67, v75, v76
	v_lshlrev_b32_e32 v64, 16, v66
	v_and_b32_e32 v71, 0xffff0000, v67
	v_mul_f32_e32 v65, v65, v65
	v_cvt_pk_bf16_f32 v68, v77, v78
	v_lshlrev_b32_e32 v70, 16, v67
	v_and_b32_e32 v74, 0xffff0000, v68
	v_mul_f32_e32 v71, v71, v71
	v_fmac_f32_e32 v65, v64, v64
	v_cvt_pk_bf16_f32 v69, v82, v79
	v_lshlrev_b32_e32 v73, 16, v68
	v_and_b32_e32 v76, 0xffff0000, v69
	v_mul_f32_e32 v74, v74, v74
	v_fmac_f32_e32 v71, v70, v70
	v_add_f32_e32 v64, v72, v65
	v_lshlrev_b32_e32 v75, 16, v69
	v_mul_f32_e32 v76, v76, v76
	v_fmac_f32_e32 v74, v73, v73
	v_add_f32_e32 v64, v64, v71
	v_add_f32_e32 v64, v64, v74
	v_fmac_f32_e32 v76, v75, v75
	v_add_f32_e32 v64, v64, v76
	ds_bpermute_b32 v65, v114, v64
	global_store_dwordx4 v[86:87], v[66:69], off offset:256
	s_waitcnt lgkmcnt(0)
	v_add_f32_e32 v64, v64, v65
	ds_bpermute_b32 v65, v115, v64
	s_and_saveexec_b64 s[44:45], s[40:41]
	s_cbranch_execz .LBB0_866
	v_lshlrev_b64 v[66:67], 6, v[80:81]
	v_lshl_add_u64 v[66:67], s[20:21], 0, v[66:67]
	v_lshl_add_u64 v[66:67], s[34:35], 2, v[66:67]
	s_lshl_b32 s36, s27, 2
	v_lshl_add_u64 v[66:67], v[66:67], 0, s[36:37]
	s_waitcnt lgkmcnt(0)
	v_add_f32_e32 v64, v64, v65
	global_store_dword v[66:67], v64, off
.LBB0_866:
	s_or_b64 exec, exec, s[44:45]
	v_add_u32_e32 v64, 0x80, v140
	s_waitcnt lgkmcnt(0)
	v_ashrrev_i32_e32 v65, 31, v64
	v_lshlrev_b64 v[66:67], 11, v[64:65]
	v_lshl_add_u64 v[66:67], s[80:81], 0, v[66:67]
	v_lshl_add_u64 v[70:71], v[138:139], 1, v[66:67]
	s_waitcnt vmcnt(19)
	v_mov_b64_e32 v[66:67], v[184:185]
	v_mov_b64_e32 v[68:69], v[186:187]
	v_lshlrev_b32_e32 v72, 16, v66
	v_and_b32_e32 v66, 0xffff0000, v66
	v_lshlrev_b32_e32 v73, 16, v67
	v_and_b32_e32 v67, 0xffff0000, v67
	v_lshlrev_b32_e32 v74, 16, v68
	v_and_b32_e32 v68, 0xffff0000, v68
	v_lshlrev_b32_e32 v75, 16, v69
	v_and_b32_e32 v69, 0xffff0000, v69
	v_fmac_f32_e32 v72, s2, v60
	v_fmac_f32_e32 v66, s2, v61
	v_fmac_f32_e32 v73, s2, v62
	v_fmac_f32_e32 v67, s2, v63
	v_fmac_f32_e32 v74, s2, v56
	v_fmac_f32_e32 v68, s2, v57
	v_fmac_f32_e32 v75, s2, v58
	v_fmac_f32_e32 v69, s2, v59
	v_cvt_pk_bf16_f32 v56, v72, v66
	v_cvt_pk_bf16_f32 v57, v73, v67
	v_cvt_pk_bf16_f32 v58, v74, v68
	v_cvt_pk_bf16_f32 v59, v75, v69
	v_and_b32_e32 v67, 0xffff0000, v56
	v_and_b32_e32 v69, 0xffff0000, v57
	v_lshlrev_b32_e32 v66, 16, v56
	v_lshlrev_b32_e32 v68, 16, v57
	v_and_b32_e32 v73, 0xffff0000, v58
	global_store_dwordx4 v[70:71], v[56:59], off
	v_lshlrev_b32_e32 v72, 16, v58
	v_and_b32_e32 v75, 0xffff0000, v59
	v_mul_f32_e32 v56, v67, v67
	v_mul_f32_e32 v57, v69, v69
	v_mul_f32_e32 v58, v73, v73
	v_fmac_f32_e32 v56, v66, v66
	v_fmac_f32_e32 v57, v68, v68
	v_lshlrev_b32_e32 v74, 16, v59
	v_mul_f32_e32 v59, v75, v75
	v_fmac_f32_e32 v58, v72, v72
	v_add_f32_e32 v56, v56, v57
	v_fmac_f32_e32 v59, v74, v74
	v_add_f32_e32 v56, v56, v58
	v_add_f32_e32 v56, v56, v59
	s_waitcnt vmcnt(19)
	v_mov_b64_e32 v[60:61], v[188:189]
	v_mov_b64_e32 v[62:63], v[190:191]
	v_lshlrev_b32_e32 v57, 16, v60
	v_and_b32_e32 v58, 0xffff0000, v60
	v_lshlrev_b32_e32 v59, 16, v61
	v_and_b32_e32 v60, 0xffff0000, v61
	v_lshlrev_b32_e32 v61, 16, v62
	v_and_b32_e32 v62, 0xffff0000, v62
	v_lshlrev_b32_e32 v66, 16, v63
	v_and_b32_e32 v63, 0xffff0000, v63
	v_fmac_f32_e32 v57, s2, v52
	v_fmac_f32_e32 v58, s2, v53
	v_fmac_f32_e32 v62, s2, v49
	v_fmac_f32_e32 v66, s2, v50
	v_cvt_pk_bf16_f32 v50, v57, v58
	v_fmac_f32_e32 v59, s2, v54
	v_and_b32_e32 v49, 0xffff0000, v50
	v_fmac_f32_e32 v60, s2, v55
	v_fmac_f32_e32 v61, s2, v48
	v_fmac_f32_e32 v63, s2, v51
	v_cvt_pk_bf16_f32 v51, v59, v60
	v_lshlrev_b32_e32 v48, 16, v50
	v_and_b32_e32 v55, 0xffff0000, v51
	v_mul_f32_e32 v49, v49, v49
	v_cvt_pk_bf16_f32 v52, v61, v62
	v_lshlrev_b32_e32 v54, 16, v51
	v_and_b32_e32 v58, 0xffff0000, v52
	v_mul_f32_e32 v55, v55, v55
	v_fmac_f32_e32 v49, v48, v48
	v_cvt_pk_bf16_f32 v53, v66, v63
	v_lshlrev_b32_e32 v57, 16, v52
	v_and_b32_e32 v60, 0xffff0000, v53
	v_mul_f32_e32 v58, v58, v58
	v_fmac_f32_e32 v55, v54, v54
	v_add_f32_e32 v48, v56, v49
	v_lshlrev_b32_e32 v59, 16, v53
	v_mul_f32_e32 v60, v60, v60
	v_fmac_f32_e32 v58, v57, v57
	v_add_f32_e32 v48, v48, v55
	v_add_f32_e32 v48, v48, v58
	v_fmac_f32_e32 v60, v59, v59
	v_add_f32_e32 v48, v48, v60
	ds_bpermute_b32 v49, v114, v48
	global_store_dwordx4 v[70:71], v[50:53], off offset:256
	s_waitcnt lgkmcnt(0)
	v_add_f32_e32 v48, v48, v49
	ds_bpermute_b32 v49, v115, v48
	s_and_saveexec_b64 s[44:45], s[40:41]
	s_cbranch_execz .LBB0_868
	v_lshlrev_b64 v[50:51], 6, v[64:65]
	v_lshl_add_u64 v[50:51], s[20:21], 0, v[50:51]
	v_lshl_add_u64 v[50:51], s[34:35], 2, v[50:51]
	s_lshl_b32 s36, s27, 2
	v_lshl_add_u64 v[50:51], v[50:51], 0, s[36:37]
	s_waitcnt lgkmcnt(0)
	v_add_f32_e32 v48, v48, v49
	global_store_dword v[50:51], v48, off
.LBB0_868:
	s_or_b64 exec, exec, s[44:45]
	v_add_u32_e32 v48, 0x90, v140
	s_waitcnt lgkmcnt(0)
	v_ashrrev_i32_e32 v49, 31, v48
	v_lshlrev_b64 v[50:51], 11, v[48:49]
	v_lshl_add_u64 v[50:51], s[80:81], 0, v[50:51]
	v_lshl_add_u64 v[54:55], v[138:139], 1, v[50:51]
	s_waitcnt vmcnt(20)
	v_mov_b64_e32 v[50:51], v[192:193]
	v_mov_b64_e32 v[52:53], v[194:195]
	v_lshlrev_b32_e32 v56, 16, v50
	v_and_b32_e32 v50, 0xffff0000, v50
	v_lshlrev_b32_e32 v57, 16, v51
	v_and_b32_e32 v51, 0xffff0000, v51
	v_lshlrev_b32_e32 v58, 16, v52
	v_and_b32_e32 v52, 0xffff0000, v52
	v_lshlrev_b32_e32 v59, 16, v53
	v_and_b32_e32 v53, 0xffff0000, v53
	v_fmac_f32_e32 v56, s2, v44
	v_fmac_f32_e32 v50, s2, v45
	v_fmac_f32_e32 v57, s2, v46
	v_fmac_f32_e32 v51, s2, v47
	v_fmac_f32_e32 v58, s2, v40
	v_fmac_f32_e32 v52, s2, v41
	v_fmac_f32_e32 v59, s2, v42
	v_fmac_f32_e32 v53, s2, v43
	v_cvt_pk_bf16_f32 v40, v56, v50
	v_cvt_pk_bf16_f32 v41, v57, v51
	v_cvt_pk_bf16_f32 v42, v58, v52
	v_cvt_pk_bf16_f32 v43, v59, v53
	v_and_b32_e32 v51, 0xffff0000, v40
	v_and_b32_e32 v53, 0xffff0000, v41
	v_lshlrev_b32_e32 v50, 16, v40
	v_lshlrev_b32_e32 v52, 16, v41
	v_and_b32_e32 v57, 0xffff0000, v42
	global_store_dwordx4 v[54:55], v[40:43], off
	v_lshlrev_b32_e32 v56, 16, v42
	v_and_b32_e32 v59, 0xffff0000, v43
	v_mul_f32_e32 v40, v51, v51
	v_mul_f32_e32 v41, v53, v53
	v_mul_f32_e32 v42, v57, v57
	v_fmac_f32_e32 v40, v50, v50
	v_fmac_f32_e32 v41, v52, v52
	v_lshlrev_b32_e32 v58, 16, v43
	v_mul_f32_e32 v43, v59, v59
	v_fmac_f32_e32 v42, v56, v56
	v_add_f32_e32 v40, v40, v41
	v_fmac_f32_e32 v43, v58, v58
	v_add_f32_e32 v40, v40, v42
	v_add_f32_e32 v40, v40, v43
	s_waitcnt vmcnt(20)
	v_mov_b64_e32 v[44:45], v[204:205]
	v_mov_b64_e32 v[46:47], v[206:207]
	v_lshlrev_b32_e32 v41, 16, v44
	v_and_b32_e32 v42, 0xffff0000, v44
	v_lshlrev_b32_e32 v43, 16, v45
	v_and_b32_e32 v44, 0xffff0000, v45
	v_lshlrev_b32_e32 v45, 16, v46
	v_and_b32_e32 v46, 0xffff0000, v46
	v_lshlrev_b32_e32 v50, 16, v47
	v_and_b32_e32 v47, 0xffff0000, v47
	v_fmac_f32_e32 v41, s2, v36
	v_fmac_f32_e32 v42, s2, v37
	v_fmac_f32_e32 v46, s2, v33
	v_fmac_f32_e32 v50, s2, v34
	v_cvt_pk_bf16_f32 v34, v41, v42
	v_fmac_f32_e32 v43, s2, v38
	v_and_b32_e32 v33, 0xffff0000, v34
	v_fmac_f32_e32 v44, s2, v39
	v_fmac_f32_e32 v45, s2, v32
	v_fmac_f32_e32 v47, s2, v35
	v_cvt_pk_bf16_f32 v35, v43, v44
	v_lshlrev_b32_e32 v32, 16, v34
	v_and_b32_e32 v39, 0xffff0000, v35
	v_mul_f32_e32 v33, v33, v33
	v_cvt_pk_bf16_f32 v36, v45, v46
	v_lshlrev_b32_e32 v38, 16, v35
	v_and_b32_e32 v42, 0xffff0000, v36
	v_mul_f32_e32 v39, v39, v39
	v_fmac_f32_e32 v33, v32, v32
	v_cvt_pk_bf16_f32 v37, v50, v47
	v_lshlrev_b32_e32 v41, 16, v36
	v_and_b32_e32 v44, 0xffff0000, v37
	v_mul_f32_e32 v42, v42, v42
	v_fmac_f32_e32 v39, v38, v38
	v_add_f32_e32 v32, v40, v33
	v_lshlrev_b32_e32 v43, 16, v37
	v_mul_f32_e32 v44, v44, v44
	v_fmac_f32_e32 v42, v41, v41
	v_add_f32_e32 v32, v32, v39
	v_add_f32_e32 v32, v32, v42
	v_fmac_f32_e32 v44, v43, v43
	v_add_f32_e32 v32, v32, v44
	ds_bpermute_b32 v33, v114, v32
	global_store_dwordx4 v[54:55], v[34:37], off offset:256
	s_waitcnt lgkmcnt(0)
	v_add_f32_e32 v32, v32, v33
	ds_bpermute_b32 v33, v115, v32
	s_and_saveexec_b64 s[44:45], s[40:41]
	s_cbranch_execz .LBB0_870
	v_lshlrev_b64 v[34:35], 6, v[48:49]
	v_lshl_add_u64 v[34:35], s[20:21], 0, v[34:35]
	v_lshl_add_u64 v[34:35], s[34:35], 2, v[34:35]
	s_lshl_b32 s36, s27, 2
	v_lshl_add_u64 v[34:35], v[34:35], 0, s[36:37]
	s_waitcnt lgkmcnt(0)
	v_add_f32_e32 v32, v32, v33
	global_store_dword v[34:35], v32, off
.LBB0_870:
	s_or_b64 exec, exec, s[44:45]
	v_add_u32_e32 v32, 0xa0, v140
	s_waitcnt lgkmcnt(0)
	v_ashrrev_i32_e32 v33, 31, v32
	v_lshlrev_b64 v[34:35], 11, v[32:33]
	v_lshl_add_u64 v[34:35], s[80:81], 0, v[34:35]
	v_lshl_add_u64 v[34:35], v[138:139], 1, v[34:35]
	s_waitcnt vmcnt(21)
	v_mov_b64_e32 v[36:37], v[208:209]
	v_mov_b64_e32 v[38:39], v[210:211]
	v_lshlrev_b32_e32 v40, 16, v36
	v_fmac_f32_e32 v40, s2, v28
	v_and_b32_e32 v28, 0xffff0000, v36
	v_fmac_f32_e32 v28, s2, v29
	v_cvt_pk_bf16_f32 v28, v40, v28
	s_nop 0
	v_and_b32_e32 v36, 0xffff0000, v28
	v_lshlrev_b32_e32 v29, 16, v28
	v_mul_f32_e32 v36, v36, v36
	v_fmac_f32_e32 v36, v29, v29
	v_lshlrev_b32_e32 v29, 16, v37
	v_fmac_f32_e32 v29, s2, v30
	v_and_b32_e32 v30, 0xffff0000, v37
	v_fmac_f32_e32 v30, s2, v31
	v_cvt_pk_bf16_f32 v29, v29, v30
	s_nop 0
	v_and_b32_e32 v31, 0xffff0000, v29
	v_lshlrev_b32_e32 v30, 16, v29
	v_mul_f32_e32 v31, v31, v31
	v_fmac_f32_e32 v31, v30, v30
	v_lshlrev_b32_e32 v30, 16, v38
	v_fmac_f32_e32 v30, s2, v24
	v_and_b32_e32 v24, 0xffff0000, v38
	v_fmac_f32_e32 v24, s2, v25
	v_cvt_pk_bf16_f32 v30, v30, v24
	v_add_f32_e32 v31, v36, v31
	v_and_b32_e32 v25, 0xffff0000, v30
	v_lshlrev_b32_e32 v24, 16, v30
	v_mul_f32_e32 v25, v25, v25
	v_fmac_f32_e32 v25, v24, v24
	v_add_f32_e32 v24, v31, v25
	v_lshlrev_b32_e32 v25, 16, v39
	v_fmac_f32_e32 v25, s2, v26
	v_and_b32_e32 v26, 0xffff0000, v39
	v_fmac_f32_e32 v26, s2, v27
	v_cvt_pk_bf16_f32 v31, v25, v26
	global_store_dwordx4 v[34:35], v[28:31], off
	v_and_b32_e32 v26, 0xffff0000, v31
	v_lshlrev_b32_e32 v25, 16, v31
	v_mul_f32_e32 v26, v26, v26
	v_fmac_f32_e32 v26, v25, v25
	v_add_f32_e32 v36, v24, v26
	s_waitcnt vmcnt(21)
	v_mov_b64_e32 v[24:25], v[212:213]
	v_mov_b64_e32 v[26:27], v[214:215]
	v_lshlrev_b32_e32 v28, 16, v24
	v_fmac_f32_e32 v28, s2, v20
	v_and_b32_e32 v20, 0xffff0000, v24
	v_fmac_f32_e32 v20, s2, v21
	v_cvt_pk_bf16_f32 v20, v28, v20
	s_nop 0
	v_and_b32_e32 v24, 0xffff0000, v20
	v_lshlrev_b32_e32 v21, 16, v20
	v_mul_f32_e32 v24, v24, v24
	v_fmac_f32_e32 v24, v21, v21
	v_lshlrev_b32_e32 v21, 16, v25
	v_fmac_f32_e32 v21, s2, v22
	v_and_b32_e32 v22, 0xffff0000, v25
	v_fmac_f32_e32 v22, s2, v23
	v_cvt_pk_bf16_f32 v21, v21, v22
	v_add_f32_e32 v24, v36, v24
	v_and_b32_e32 v23, 0xffff0000, v21
	v_lshlrev_b32_e32 v22, 16, v21
	v_mul_f32_e32 v23, v23, v23
	v_fmac_f32_e32 v23, v22, v22
	v_lshlrev_b32_e32 v22, 16, v26
	v_fmac_f32_e32 v22, s2, v16
	v_and_b32_e32 v16, 0xffff0000, v26
	v_fmac_f32_e32 v16, s2, v17
	v_cvt_pk_bf16_f32 v22, v22, v16
	v_add_f32_e32 v23, v24, v23
	v_and_b32_e32 v17, 0xffff0000, v22
	v_lshlrev_b32_e32 v16, 16, v22
	v_mul_f32_e32 v17, v17, v17
	v_fmac_f32_e32 v17, v16, v16
	v_add_f32_e32 v16, v23, v17
	v_lshlrev_b32_e32 v17, 16, v27
	v_fmac_f32_e32 v17, s2, v18
	v_and_b32_e32 v18, 0xffff0000, v27
	v_fmac_f32_e32 v18, s2, v19
	v_cvt_pk_bf16_f32 v23, v17, v18
	global_store_dwordx4 v[34:35], v[20:23], off offset:256
	v_and_b32_e32 v18, 0xffff0000, v23
	v_lshlrev_b32_e32 v17, 16, v23
	v_mul_f32_e32 v18, v18, v18
	v_fmac_f32_e32 v18, v17, v17
	v_add_f32_e32 v16, v16, v18
	ds_bpermute_b32 v17, v114, v16
	s_waitcnt lgkmcnt(0)
	v_add_f32_e32 v16, v16, v17
	ds_bpermute_b32 v17, v115, v16
	s_and_saveexec_b64 s[44:45], s[40:41]
	s_cbranch_execz .LBB0_872
	v_lshlrev_b64 v[18:19], 6, v[32:33]
	v_lshl_add_u64 v[18:19], s[20:21], 0, v[18:19]
	v_lshl_add_u64 v[18:19], s[34:35], 2, v[18:19]
	s_lshl_b32 s36, s27, 2
	v_lshl_add_u64 v[18:19], v[18:19], 0, s[36:37]
	s_waitcnt lgkmcnt(0)
	v_add_f32_e32 v16, v16, v17
	global_store_dword v[18:19], v16, off
.LBB0_872:
	s_or_b64 exec, exec, s[44:45]
	v_add_u32_e32 v16, 0xb0, v140
	s_waitcnt lgkmcnt(0)
	v_ashrrev_i32_e32 v17, 31, v16
	v_lshlrev_b64 v[18:19], 11, v[16:17]
	v_lshl_add_u64 v[18:19], s[80:81], 0, v[18:19]
	v_lshl_add_u64 v[22:23], v[138:139], 1, v[18:19]
	s_waitcnt vmcnt(22)
	v_mov_b64_e32 v[18:19], v[216:217]
	v_mov_b64_e32 v[20:21], v[218:219]
	v_lshlrev_b32_e32 v24, 16, v18
	v_and_b32_e32 v18, 0xffff0000, v18
	v_lshlrev_b32_e32 v25, 16, v19
	v_and_b32_e32 v19, 0xffff0000, v19
	v_lshlrev_b32_e32 v26, 16, v20
	v_and_b32_e32 v20, 0xffff0000, v20
	v_lshlrev_b32_e32 v27, 16, v21
	v_and_b32_e32 v21, 0xffff0000, v21
	v_fmac_f32_e32 v24, s2, v12
	v_fmac_f32_e32 v18, s2, v13
	v_fmac_f32_e32 v25, s2, v14
	v_fmac_f32_e32 v19, s2, v15
	v_fmac_f32_e32 v26, s2, v8
	v_fmac_f32_e32 v20, s2, v9
	v_fmac_f32_e32 v27, s2, v10
	v_fmac_f32_e32 v21, s2, v11
	v_cvt_pk_bf16_f32 v8, v24, v18
	v_cvt_pk_bf16_f32 v9, v25, v19
	v_cvt_pk_bf16_f32 v10, v26, v20
	v_cvt_pk_bf16_f32 v11, v27, v21
	v_and_b32_e32 v19, 0xffff0000, v8
	v_and_b32_e32 v21, 0xffff0000, v9
	v_lshlrev_b32_e32 v18, 16, v8
	v_lshlrev_b32_e32 v20, 16, v9
	v_and_b32_e32 v25, 0xffff0000, v10
	global_store_dwordx4 v[22:23], v[8:11], off
	v_lshlrev_b32_e32 v24, 16, v10
	v_and_b32_e32 v27, 0xffff0000, v11
	v_mul_f32_e32 v8, v19, v19
	v_mul_f32_e32 v9, v21, v21
	v_mul_f32_e32 v10, v25, v25
	v_fmac_f32_e32 v8, v18, v18
	v_fmac_f32_e32 v9, v20, v20
	v_lshlrev_b32_e32 v26, 16, v11
	v_mul_f32_e32 v11, v27, v27
	v_fmac_f32_e32 v10, v24, v24
	v_add_f32_e32 v8, v8, v9
	v_fmac_f32_e32 v11, v26, v26
	v_add_f32_e32 v8, v8, v10
	v_add_f32_e32 v8, v8, v11
	s_waitcnt vmcnt(22)
	v_mov_b64_e32 v[12:13], v[228:229]
	v_mov_b64_e32 v[14:15], v[230:231]
	v_lshlrev_b32_e32 v9, 16, v12
	v_and_b32_e32 v10, 0xffff0000, v12
	v_lshlrev_b32_e32 v11, 16, v13
	v_and_b32_e32 v12, 0xffff0000, v13
	v_lshlrev_b32_e32 v13, 16, v14
	v_and_b32_e32 v14, 0xffff0000, v14
	v_lshlrev_b32_e32 v18, 16, v15
	v_and_b32_e32 v15, 0xffff0000, v15
	v_fmac_f32_e32 v9, s2, v4
	v_fmac_f32_e32 v10, s2, v5
	v_fmac_f32_e32 v14, s2, v1
	v_fmac_f32_e32 v18, s2, v2
	v_cvt_pk_bf16_f32 v2, v9, v10
	v_fmac_f32_e32 v11, s2, v6
	v_and_b32_e32 v1, 0xffff0000, v2
	v_fmac_f32_e32 v12, s2, v7
	v_fmac_f32_e32 v13, s2, v0
	v_fmac_f32_e32 v15, s2, v3
	v_cvt_pk_bf16_f32 v3, v11, v12
	v_lshlrev_b32_e32 v0, 16, v2
	v_and_b32_e32 v7, 0xffff0000, v3
	v_mul_f32_e32 v1, v1, v1
	v_cvt_pk_bf16_f32 v4, v13, v14
	v_lshlrev_b32_e32 v6, 16, v3
	v_and_b32_e32 v10, 0xffff0000, v4
	v_mul_f32_e32 v7, v7, v7
	v_fmac_f32_e32 v1, v0, v0
	v_cvt_pk_bf16_f32 v5, v18, v15
	v_lshlrev_b32_e32 v9, 16, v4
	v_and_b32_e32 v12, 0xffff0000, v5
	v_mul_f32_e32 v10, v10, v10
	v_fmac_f32_e32 v7, v6, v6
	v_add_f32_e32 v0, v8, v1
	v_lshlrev_b32_e32 v11, 16, v5
	v_mul_f32_e32 v12, v12, v12
	v_fmac_f32_e32 v10, v9, v9
	v_add_f32_e32 v0, v0, v7
	v_add_f32_e32 v0, v0, v10
	v_fmac_f32_e32 v12, v11, v11
	v_add_f32_e32 v0, v0, v12
	ds_bpermute_b32 v1, v114, v0
	global_store_dwordx4 v[22:23], v[2:5], off offset:256
	s_waitcnt lgkmcnt(0)
	v_add_f32_e32 v0, v0, v1
	ds_bpermute_b32 v1, v115, v0
	s_and_saveexec_b64 s[44:45], s[40:41]
	s_cbranch_execz .LBB0_874
	v_lshlrev_b64 v[2:3], 6, v[16:17]
	v_lshl_add_u64 v[2:3], s[20:21], 0, v[2:3]
	v_lshl_add_u64 v[2:3], s[34:35], 2, v[2:3]
	s_lshl_b32 s36, s27, 2
	v_lshl_add_u64 v[2:3], v[2:3], 0, s[36:37]
	s_waitcnt lgkmcnt(0)
	v_add_f32_e32 v0, v0, v1
	global_store_dword v[2:3], v0, off
